# DSA_IN: tiles rebalanced to 464 per XCD (rows 80..127 of n-tile columns 24..28 moved to the XCDs that owned 3 columns)
# speedup vs baseline: 1.0056x; 1.0056x over previous
; DI unsigned xb_ld(unsigned* p)              { return __hip_atomic_load(p, __ATOMIC_RELAXED, __HIP_MEMORY_SCOPE_AGENT); }
; DI unsigned xb_xcc_id() { return (unsigned)__builtin_amdgcn_s_getreg((3 << 11) | 20) & 0xFu; }
;     ...
;   if constexpr (EPI == EPI_DSA_IN) {
;     int* sl = (int*)(smem + 40960);
;     __syncthreads();
;     if (tid == 0) {
;       unsigned* bar = (unsigned*)(ws + OFF_BAR);
;       const unsigned myx = xb_xcc_id();
;       int nx = 0, xo = 0, nloc = 1;
;       for (unsigned j = 0; j < 16; ++j) { const unsigned cj = xb_ld(&bar[XB_XCNT(j)]); if (cj > 0u) { if (j == myx) { xo = nx; nloc = (int)cj; } ++nx; } }
;       sl[0] = (int)atomicAdd((u32*)(ws + OFF_CTR) + 128 + myx, 1u);
;       sl[1] = nloc; sl[2] = xo; sl[3] = nx;
;     }
;     __syncthreads();
;     if (sl[3] == 8) {
;       xi = sl[2];
;       cntS = (Ntiles - 1 - xi) / 8 + 1;
;       t_start = sl[0]; t_step = sl[1]; t_total = 128 * cntS;
;     }
;     __syncthreads();
;   }
.LBB0_940:
	s_or_b64 exec, exec, s[10:11]
	v_mov_b32_e32 v1, 0
	s_waitcnt lgkmcnt(0)
	s_barrier
	ds_read_b32 v2, v1 offset:40972
	s_waitcnt lgkmcnt(0)
	v_cmp_ne_u32_e32 vcc, 8, v2
	s_cbranch_vccnz .LBB0_942
	ds_read_b96 v[2:4], v1 offset:40960
	s_waitcnt lgkmcnt(0)
	v_readfirstlane_b32 s52, v4
	s_sub_i32 s4, 28, s52
	s_ashr_i32 s5, s4, 31
	s_lshr_b32 s5, s5, 29
	s_add_i32 s4, s4, s5
	s_ashr_i32 s4, s4, 3
	s_add_i32 s56, s4, 1
	v_readfirstlane_b32 s53, v2
	v_readfirstlane_b32 s54, v3
	s_lshl_b32 s55, s56, 7
	s_cmp_eq_u32 s26, 0x200
	s_cselect_b32 s55, 0x1d0, s55
	s_branch .LBB0_943

; DI int opaque_tid() { int t = threadIdx.x; asm volatile("" : "+v"(t)); return t; }
; DI void gemm_mainloop(const bf16* __restrict__ A, int lda, const bf16* __restrict__ Bt, int ldb, int K, int m0, int n0,
;                       bf16* As, bf16* Bs, f32x16& acc0, f32x16& acc1, f32x16& acc2, f32x16& acc3) {
;   const int tid = opaque_tid(), lane = tid & 63, w = tid >> 6, r = lane & 31, g = lane >> 5;
;   const int lrow = tid >> 3, lcc = (tid & 7) * 8;
;   const bf16* ap = A + (size_t)(m0 + lrow) * lda + lcc;
;   const bf16* bp = Bt + (size_t)(n0 + lrow) * ldb + lcc;
;   GTile t0, t1;
;   asm volatile("" ::: "memory");
;   const int nkt = K >> 6;
;   int kb = ((((m0 >> 7) * 5 + (n0 >> 7) * 3) >> 1) % nkt) << 6;
;     ...
;   gt_load(t0, ap, bp, lda, ldb, KW(0));
;   gt_load(t1, ap, bp, lda, ldb, KW(64));
; #pragma unroll
;   for (int i = 0; i < 16; ++i) { acc0[i] = 0.f; acc1[i] = 0.f; acc2[i] = 0.f; acc3[i] = 0.f; }
;     ...
;   for (int tile = t_start; tile < t_total; tile += t_step) {
;     int mt, nt;
;     if (cntS) { mt = tile / cntS; nt = xi + 8 * (tile % cntS); } else { mt = tile / Ntiles; nt = tile % Ntiles; }
;     const int m0 = mt * 128, n0 = nt * 128;
.LBB0_949:
	s_abs_i32 s14, s7
	v_cvt_f32_u32_e32 v0, s14
	s_ashr_i32 s7, s7, 31
	s_xor_b32 s6, s6, s7
	s_sub_i32 s7, 0, s14
	v_rcp_iflag_f32_e32 v0, v0
	v_mov_b32_e32 v8, v160
	v_mul_f32_e32 v0, 0x4f7ffffe, v0
	v_cvt_u32_f32_e32 v0, v0
	v_ashrrev_i32_e32 v9, 3, v8
	v_lshlrev_b32_e32 v2, 4, v8
	v_and_b32_e32 v130, 0x70, v2
	v_readfirstlane_b32 s28, v0
	s_mul_i32 s7, s7, s28
	s_mul_hi_u32 s7, s28, s7
	s_add_i32 s28, s28, s7
	s_mul_i32 s7, s15, s28
	s_mul_hi_u32 s28, s5, s28
	s_add_i32 s7, s28, s7
	s_mul_i32 s28, s7, s14
	s_sub_i32 s5, s5, s28
	s_add_i32 s29, s7, 1
	s_sub_i32 s28, s5, s14
	s_cmp_ge_u32 s5, s14
	s_cselect_b32 s7, s29, s7
	s_cselect_b32 s5, s28, s5
	s_add_i32 s28, s7, 1
	s_cmp_ge_u32 s5, s14
	s_cselect_b32 s5, s28, s7
	s_xor_b32 s5, s5, s6
	s_sub_i32 s14, s5, s6
	s_cmp_lg_u32 s26, 0x200
	s_cbranch_scc1 .Lmy_rb_end
	s_cmp_eq_u32 s56, 0
	s_cbranch_scc1 .Lmy_rb_end
	s_cmp_gt_u32 s52, 4
	s_cbranch_scc1 .Lmy_rb_hi
	s_cmpk_lt_u32 s53, 0x140
	s_cbranch_scc0 .Lmy_rb_lo2
	s_lshr_b32 s14, s53, 2
	s_and_b32 s98, s53, 3
	s_branch .Lmy_rb_fin
.Lmy_rb_lo2:
	s_sub_u32 s98, s53, 0x140
	s_mul_i32 s99, s98, 0x5556
	s_lshr_b32 s99, s99, 16
	s_mul_i32 s100, s99, 3
	s_sub_u32 s98, s98, s100
	s_add_u32 s14, s99, 0x50
	s_branch .Lmy_rb_fin
.Lmy_rb_hi:
	s_cmpk_lt_u32 s53, 0x180
	s_cbranch_scc0 .Lmy_rb_hi2
	s_mul_i32 s99, s53, 0x5556
	s_lshr_b32 s14, s99, 16
	s_mul_i32 s100, s14, 3
	s_sub_u32 s98, s53, s100
.Lmy_rb_fin:
	s_lshl_b32 s98, s98, 3
	s_add_u32 s4, s98, s52
	s_branch .Lmy_rb_end
.Lmy_rb_hi2:
	s_sub_u32 s98, s53, 0x180
	s_cmp_eq_u32 s52, 5
	s_cbranch_scc0 .Lmy_rb_x6
	s_cmp_lt_u32 s98, 48
	s_cselect_b32 s4, 24, 25
	s_cselect_b32 s99, 0x50, 32
	s_add_u32 s14, s98, s99
	s_branch .Lmy_rb_end
.Lmy_rb_x6:
	s_cmp_eq_u32 s52, 6
	s_cbranch_scc0 .Lmy_rb_x7
	s_cmp_lt_u32 s98, 64
	s_cselect_b32 s4, 26, 27
	s_cselect_b32 s99, 64, 16
	s_cmp_lt_u32 s98, 16
	s_cselect_b32 s4, 25, s4
	s_cselect_b32 s99, 0x70, s99
	s_add_u32 s14, s98, s99
	s_branch .Lmy_rb_end
.Lmy_rb_x7:
	s_cmp_lt_u32 s98, 32
	s_cselect_b32 s4, 27, 28
	s_cselect_b32 s99, 0x60, 48
	s_add_u32 s14, s98, s99
.Lmy_rb_end:
	s_mul_i32 s6, s14, 5
	s_mul_i32 s7, s4, 3
	s_lshl_b32 s5, s14, 7
	s_add_i32 s6, s6, s7
	v_add_u32_e32 v0, s5, v9
	s_ashr_i32 s7, s6, 1
	s_ashr_i32 s6, s6, 31
	v_ashrrev_i32_e32 v1, 31, v0
	s_lshr_b32 s6, s6, 28
	v_lshlrev_b64 v[0:1], 11, v[0:1]
	s_add_i32 s6, s7, s6
	v_lshl_add_u64 v[0:1], s[38:39], 0, v[0:1]
	s_and_b32 s6, s6, -16
	v_lshl_add_u64 v[146:147], v[0:1], 0, v[130:131]
	v_lshl_add_u32 v0, s4, 7, v9
	s_sub_i32 s30, s7, s6
	v_ashrrev_i32_e32 v1, 31, v0
	s_lshl_b32 s28, s30, 6
	v_lshlrev_b64 v[0:1], 11, v[0:1]
	s_ashr_i32 s29, s28, 31
	v_lshl_add_u64 v[0:1], s[12:13], 0, v[0:1]
	s_lshl_b64 s[6:7], s[28:29], 1
	v_lshl_add_u64 v[148:149], v[0:1], 0, v[130:131]
	v_lshl_add_u64 v[0:1], v[146:147], 0, s[6:7]
	v_add_co_u32_e32 v4, vcc, s59, v0
	v_lshl_add_u64 v[2:3], v[148:149], 0, s[6:7]
	s_nop 0
	v_addc_co_u32_e32 v5, vcc, 0, v1, vcc
	v_add_co_u32_e32 v6, vcc, s60, v0
	s_cmp_lt_i32 s30, 15
	s_nop 0
	v_addc_co_u32_e32 v7, vcc, 0, v1, vcc
	global_load_dwordx4 v[64:67], v[4:5], off
	global_load_dwordx4 v[68:71], v[6:7], off
	v_add_co_u32_e32 v4, vcc, s61, v0
	global_load_dwordx4 v[72:75], v[0:1], off
	global_load_dwordx4 v[76:79], v[2:3], off
	v_addc_co_u32_e32 v5, vcc, 0, v1, vcc
	v_add_co_u32_e32 v6, vcc, s59, v2
	s_cselect_b32 s7, 0, -1
	s_nop 0
	v_addc_co_u32_e32 v7, vcc, 0, v3, vcc
	global_load_dwordx4 v[80:83], v[4:5], off
	global_load_dwordx4 v[84:87], v[6:7], off
	v_add_co_u32_e32 v4, vcc, s60, v2
	s_cselect_b32 s6, 0, 0xfffff800
	s_nop 0
	v_addc_co_u32_e32 v5, vcc, 0, v3, vcc
	v_add_co_u32_e32 v6, vcc, s61, v2
	v_lshl_add_u64 v[0:1], v[0:1], 0, s[6:7]
	s_nop 0
	v_addc_co_u32_e32 v7, vcc, 0, v3, vcc
	global_load_dwordx4 v[96:99], v[4:5], off
	global_load_dwordx4 v[104:107], v[6:7], off
	v_add_co_u32_e32 v4, vcc, s59, v0
	v_lshl_add_u64 v[2:3], v[2:3], 0, s[6:7]
	s_nop 0
	v_addc_co_u32_e32 v5, vcc, 0, v1, vcc
	v_add_co_u32_e32 v6, vcc, s60, v0
	v_mad_u64_u32 v[150:151], s[6:7], v9, s62, v[130:131]
	s_nop 0
	v_addc_co_u32_e32 v7, vcc, 0, v1, vcc
	global_load_dwordx4 v[88:91], v[4:5], off offset:128
	global_load_dwordx4 v[92:95], v[6:7], off offset:128
	v_add_co_u32_e32 v4, vcc, s61, v0
	global_load_dwordx4 v[100:103], v[0:1], off offset:128
	global_load_dwordx4 v[108:111], v[2:3], off offset:128
	v_addc_co_u32_e32 v5, vcc, 0, v1, vcc
	v_add_co_u32_e32 v0, vcc, s59, v2
	s_sub_i32 s30, 0x400, s28
	s_nop 0
	v_addc_co_u32_e32 v1, vcc, 0, v3, vcc
	global_load_dwordx4 v[112:115], v[4:5], off offset:128
	global_load_dwordx4 v[116:119], v[0:1], off offset:128
	v_add_co_u32_e32 v0, vcc, s60, v2
	s_sub_i32 s31, 0x340, s28
	s_nop 0
	v_addc_co_u32_e32 v1, vcc, 0, v3, vcc
	v_add_co_u32_e32 v2, vcc, s61, v2
	s_mov_b64 s[48:49], 0
	s_nop 0
	v_addc_co_u32_e32 v3, vcc, 0, v3, vcc
	global_load_dwordx4 v[120:123], v[0:1], off offset:128
	global_load_dwordx4 v[124:127], v[2:3], off offset:128
	v_and_b32_e32 v1, 31, v8
	v_lshrrev_b32_e32 v0, 1, v8
	v_and_or_b32 v2, v0, s63, v1
	v_and_b32_e32 v0, 16, v0
	v_mad_u64_u32 v[152:153], s[6:7], v2, s62, v[0:1]
	v_mad_u32_u24 v130, v1, s62, v0
	v_mov_b32_e32 v0, 0
	v_mov_b32_e32 v1, v0
	v_mov_b32_e32 v2, v0
	v_mov_b32_e32 v3, v0
	v_mov_b32_e32 v4, v0
	v_mov_b32_e32 v5, v0
	v_mov_b32_e32 v6, v0
	v_mov_b32_e32 v7, v0
	v_mov_b32_e32 v8, v0
	v_mov_b32_e32 v9, v0
	v_mov_b32_e32 v10, v0
	v_mov_b32_e32 v11, v0
	v_mov_b32_e32 v12, v0
	v_mov_b32_e32 v13, v0
	v_mov_b32_e32 v14, v0
	v_mov_b32_e32 v15, v0
	v_mov_b32_e32 v32, v0
	v_mov_b32_e32 v33, v0
	v_mov_b32_e32 v34, v0
	v_mov_b32_e32 v35, v0
	v_mov_b32_e32 v36, v0
	v_mov_b32_e32 v37, v0
	v_mov_b32_e32 v38, v0
	v_mov_b32_e32 v39, v0
	v_mov_b32_e32 v40, v0
	v_mov_b32_e32 v41, v0
	v_mov_b32_e32 v42, v0
	v_mov_b32_e32 v43, v0
	v_mov_b32_e32 v44, v0
	v_mov_b32_e32 v45, v0
	v_mov_b32_e32 v46, v0
	v_mov_b32_e32 v47, v0
	v_mov_b32_e32 v16, v0
	v_mov_b32_e32 v17, v0
	v_mov_b32_e32 v18, v0
	v_mov_b32_e32 v19, v0
	v_mov_b32_e32 v20, v0
	v_mov_b32_e32 v21, v0
	v_mov_b32_e32 v22, v0
	v_mov_b32_e32 v23, v0
	v_mov_b32_e32 v24, v0
	v_mov_b32_e32 v25, v0
	v_mov_b32_e32 v26, v0
	v_mov_b32_e32 v27, v0
	v_mov_b32_e32 v28, v0
	v_mov_b32_e32 v29, v0
	v_mov_b32_e32 v30, v0
	v_mov_b32_e32 v31, v0
	v_mov_b32_e32 v48, v0
	v_mov_b32_e32 v49, v0
	v_mov_b32_e32 v50, v0
	v_mov_b32_e32 v51, v0
	v_mov_b32_e32 v52, v0
	v_mov_b32_e32 v53, v0
	v_mov_b32_e32 v54, v0
	v_mov_b32_e32 v55, v0
	v_mov_b32_e32 v56, v0
	v_mov_b32_e32 v57, v0
	v_mov_b32_e32 v58, v0
	v_mov_b32_e32 v59, v0
	v_mov_b32_e32 v60, v0
	v_mov_b32_e32 v61, v0
	v_mov_b32_e32 v62, v0
	v_mov_b32_e32 v63, v0
	s_branch .LBB0_951
